# P7: SSD-scan items redistributed (one item on the 128 workgroups that also run the sample attention, three on the others)
# baseline (speedup 1.0000x reference)
; #define LAS __attribute__((address_space(3)))
; __device__ __forceinline__ void ph_ssd_scan(const float* DT, const bf16* XT, const bf16* BT, bf16* HST, const float* state_ssm, const float* a_log, float* ssm_p, float* ssm_s, LAS unsigned char* lds, int vcu, int G, int tid) {
;     asm volatile("" : "+v"(tid)); const int lane = tid & 63, wave = __builtin_amdgcn_readfirstlane(tid >> 6);
;     const int fr = lane & 15, fq = lane >> 4;
;     for (int it = vcu; it < 512; it += G) {
;         const bool smp = it >= 256; const int id = it & 255, b = id >> 5, h = (id >> 2) & 7, pq = id & 3, g = h >> 2;
;         const float A = -__expf(a_log[h]);
;         const int p = pq * 16 + fr, n0 = 16 * wave + 4 * fq;
;         f32x4 hst = (f32x4){0.f, 0.f, 0.f, 0.f};
;         if (smp) hst = *(const f32x4*)(state_ssm + ((size_t)(b * 8 + h) * 64 + p) * 128 + n0);
;         const int nch = smp ? 1 : 64, ci0 = smp ? 512 + b : b * 64;
;         LAS float* sWg = (LAS float*)lds;
;         LAS float* sDec = (LAS float*)(lds + 16384);
;         __syncthreads();
;         for (int c = wave; c < nch; c += NWAVES) { const float dtv = DT[(size_t)((ci0 + c) * 64 + lane) * 8 + h]; const float a = wave_incl_scan(dtv * A, lane); const float tot = __shfl(a, 63);
;             sWg[c * 64 + lane] = dtv * __expf(tot - a); if (lane == 0) sDec[c] = __expf(tot); }
.LBB0_904:
	v_readlane_b32 s4, v254, 0
	s_cmp_lt_i32 s4, 8
	v_readlane_b32 s5, v254, 1
	s_cselect_b64 s[2:3], -1, 0
	s_and_b64 s[4:5], s[2:3], s[0:1]
	v_readlane_b32 s6, v254, 2
	v_readlane_b32 s7, v254, 3
	s_andn2_b64 vcc, exec, s[4:5]
	v_writelane_b32 v254, s92, 13
	s_cbranch_vccnz .LBB0_1105
	s_load_dwordx2 s[0:1], s[58:59], 32
	s_waitcnt lgkmcnt(0)
	s_load_dwordx2 s[10:11], s[58:59], 0x90
	s_waitcnt lgkmcnt(0)
	v_writelane_b32 v254, s4, 14
	v_mov_b32_e32 v1, v252
	s_cmpk_gt_i32 s92, 0x1ff
	v_writelane_b32 v254, s5, 15
	s_nop 0
	v_readfirstlane_b32 s2, v1
	s_cbranch_scc1 .LBB0_925
	s_waitcnt lgkmcnt(0)
	s_add_u32 s3, s66, 0x200000
	v_writelane_b32 v254, s3, 16
	s_addc_u32 s3, s67, 0
	s_add_u32 s4, s66, 0x16400000
	s_addc_u32 s5, s67, 0
	s_ashr_i32 s12, s2, 6
	v_bfe_u32 v3, v1, 4, 2
	s_lshl_b32 s2, s12, 4
	v_lshl_or_b32 v102, v3, 2, s2
	v_ashrrev_i32_e32 v103, 31, v102
	v_mov_b32_e32 v0, 0
	v_lshl_add_u64 v[104:105], v[102:103], 2, s[0:1]
	s_ashr_i32 s0, s2, 31
	v_and_b32_e32 v108, 48, v1
	v_mov_b32_e32 v109, v0
	v_mov_b32_e32 v107, s0
	v_lshl_add_u64 v[4:5], s[66:67], 0, v[108:109]
	s_mov_b64 s[0:1], 0x1a700000
	v_and_b32_e32 v129, 15, v1
	v_lshl_add_u64 v[110:111], v[4:5], 0, s[0:1]
	v_mov_b64_e32 v[4:5], 0x1b800000
	s_add_i32 s1, s12, 8
	v_lshl_add_u64 v[114:115], v[102:103], 1, v[4:5]
	s_lshl_b32 s29, s1, 8
	v_lshl_or_b32 v4, s1, 4, v129
	s_add_i32 s1, s12, 16
	s_lshl_b32 s31, s1, 8
	v_lshl_or_b32 v5, s1, 4, v129
	s_add_i32 s1, s12, 24
	v_and_b32_e32 v128, 63, v1
	v_or_b32_e32 v106, s2, v129
	v_add_u32_e32 v1, 0, v108
	s_movk_i32 s0, 0x90
	v_lshl_or_b32 v6, s1, 4, v129
	v_writelane_b32 v254, s3, 17
	v_lshlrev_b32_e32 v2, 3, v3
	v_lshl_add_u32 v130, v3, 5, 0
	v_mul_lo_u32 v3, v106, s0
	v_mul_lo_u32 v4, v4, s0
	v_mul_lo_u32 v5, v5, s0
	v_mul_lo_u32 v6, v6, s0
	v_mad_u32_u24 v131, v129, s0, v1
	s_lshl_b32 s0, s12, 2
	v_writelane_b32 v254, s4, 18
	s_add_i32 s0, s0, 0
	s_addk_i32 s0, 0x4000
	v_writelane_b32 v254, s5, 19
	v_writelane_b32 v254, s0, 20
	v_writelane_b32 v254, s10, 21
	v_cmp_eq_u32_e64 s[14:15], 0, v128
	v_cmp_gt_u32_e64 s[16:17], 2, v128
	v_writelane_b32 v254, s11, 22
	v_writelane_b32 v254, s12, 23
	v_writelane_b32 v254, s14, 24
	v_cmp_gt_u32_e64 s[18:19], 4, v128
	v_cmp_gt_u32_e64 s[22:23], 8, v128
	v_writelane_b32 v254, s15, 25
	v_writelane_b32 v254, s16, 26
	v_cmp_gt_u32_e64 s[24:25], 16, v128
	v_cmp_gt_u32_e64 s[26:27], 32, v128
	v_writelane_b32 v254, s17, 27
	v_writelane_b32 v254, s18, 28
	s_lshl_b32 s13, s12, 8
	v_add_u32_e32 v140, v1, v3
	v_writelane_b32 v254, s19, 29
	v_writelane_b32 v254, s22, 30
	v_add_u32_e32 v141, v1, v4
	v_add_u32_e32 v142, v1, v5
	v_writelane_b32 v254, s23, 31
	v_writelane_b32 v254, s24, 32
	v_add_u32_e32 v143, v1, v6
	v_mbcnt_lo_u32_b32 v1, -1, 0
	v_writelane_b32 v254, s25, 33
	v_writelane_b32 v254, s26, 34
	s_add_i32 s0, s13, 0
	v_lshlrev_b64 v[118:119], 7, v[106:107]
	v_lshlrev_b32_e32 v7, 6, v129
	s_lshl_b32 s30, s69, 4
	s_cmp_lg_u32 s69, 0x100
	s_cbranch_scc1 .Lscan_std
	s_mov_b32 s30, 0x800
	s_cmp_lt_u32 s92, 0x80
	s_cselect_b32 s30, 0x2000, s30
.Lscan_std:
	v_lshlrev_b32_e32 v8, 7, v129
	v_mbcnt_hi_u32_b32 v146, -1, v1
	v_bfrev_b32_e32 v1, 0.5
	v_writelane_b32 v254, s27, 35
	s_mov_b32 s21, 0
	v_lshl_add_u64 v[112:113], s[4:5], 0, v[108:109]
	v_lshl_add_u64 v[116:117], s[66:67], 0, v[114:115]
	s_lshl_b32 s35, s1, 8
	v_add_u32_e32 v132, 0x8000, v131
	v_add_u32_e32 v133, 0x18500, v131
	v_add_u32_e32 v134, 0x18540, v131
	v_add_u32_e32 v135, 0x18e00, v131
	v_add_u32_e32 v136, 0x18e40, v131
	v_add_u32_e32 v137, 0x19700, v131
	v_add_u32_e32 v138, 0x19740, v131
	v_lshl_add_u32 v139, v128, 2, s0
	v_or_b32_e32 v118, v118, v108
	s_lshl_b32 s28, s92, 4
	v_lshlrev_b32_e32 v144, 1, v7
	v_lshlrev_b32_e32 v145, 1, v8
	v_lshlrev_b32_e32 v120, 1, v2
	v_lshl_or_b32 v147, v146, 2, v1
	s_mov_b32 s34, s92
	v_writelane_b32 v254, s30, 36
	s_branch .LBB0_909

; __device__ __forceinline__ void ph_ssd_scan(const float* DT, const bf16* XT, const bf16* BT, bf16* HST, const float* state_ssm, const float* a_log, float* ssm_p, float* ssm_s, LAS unsigned char* lds, int vcu, int G, int tid) {
;     ...
;     for (int it = vcu; it < 512; it += G) {
;     ...
;         float* dst = smp ? ssm_s : ssm_p;
;         *(f32x4*)(dst + ((size_t)(b * 8 + h) * 64 + p) * 128 + n0) = hst;
;     }
.LBB0_908:
	s_waitcnt lgkmcnt(0)
	s_add_u32 s0, s64, s0
	s_addc_u32 s1, s65, s1
	s_lshl_b32 s2, s36, 9
	s_lshl_b32 s3, s33, 6
	s_or_b32 s2, s2, s3
	v_or_b32_e32 v1, s2, v148
	v_lshlrev_b32_e32 v2, 9, v1
	v_mov_b32_e32 v3, v0
	v_lshl_add_u64 v[2:3], s[0:1], 0, v[2:3]
	s_lshr_b32 s3, s30, 4
	s_add_i32 s34, s34, s3
	s_add_i32 s28, s28, s30
	v_lshl_add_u64 v[2:3], v[102:103], 2, v[2:3]
	s_cmpk_lt_i32 s34, 0x200
	global_store_dwordx4 v[2:3], v[62:65], off
	s_cbranch_scc0 .LBB0_925
